# static s_setprio 1 for waves 4-7 during MLA attention phase (de-sync the two waves of each SIMD)
# baseline (speedup 1.0000x reference)
.LBB0_1571:
	v_readfirstlane_b32 vcc_lo, v0
	s_nop 3
	s_bitcmp1_b32 vcc_lo, 8
	s_cbranch_scc0 .Lprio_skip_12
	s_setprio 1

.LBB0_1605:
	s_cmp_gt_i32 s77, 13
	s_cselect_b64 s[0:1], -1, 0
	s_and_b64 s[2:3], s[4:5], s[0:1]
	s_andn2_b64 vcc, exec, s[2:3]
	s_cbranch_vccnz .LBB0_1655
	s_setprio 0
	s_waitcnt vmcnt(0)
	v_cmp_eq_u32_e32 vcc, 0, v0
	s_waitcnt vmcnt(0) lgkmcnt(0)
	s_barrier
	s_and_saveexec_b64 s[2:3], vcc
	s_cbranch_execz .LBB0_1654
	v_readlane_b32 s4, v254, 13
	s_waitcnt vmcnt(0) expcnt(0) lgkmcnt(0)
	s_nop 0
	v_mov_b32_e32 v2, s4
	ds_read_b32 v4, v2
	ds_read_b32 v2, v2 offset:4
	s_waitcnt lgkmcnt(1)
	v_cmp_ne_u32_e32 vcc, 0, v4
	s_cbranch_vccnz .LBB0_1622
	v_readlane_b32 s4, v254, 11
	v_readlane_b32 s5, v254, 12
	s_load_dwordx2 s[8:9], s[4:5], 0x4
	s_add_u32 s4, s78, 0x1000
	s_addc_u32 s5, s79, 0
	s_add_u32 s6, s78, 0x1100
	s_addc_u32 s7, s79, 0
	s_waitcnt lgkmcnt(0)
	s_mul_i32 s18, s8, s96
	s_add_u32 s8, s78, 0x1200
	s_mul_i32 s18, s18, s9
	s_addc_u32 s9, s79, 0
	s_add_u32 s10, s78, 0x1300
	s_addc_u32 s11, s79, 0
	s_mov_b32 s19, 1
	v_mov_b32_e32 v18, 0
	s_branch .LBB0_1610
